# strategy 7: p3a S1 q/k image-store address arithmetic hoisted into offset:N immediates (tokens 1-7 reuse token-0 addresses)
# speedup vs baseline: 1.0119x; 1.0023x over previous
.LBB0_502:
	s_or_b64 exec, exec, s[8:9]
	v_lshrrev_b32_e32 v24, 1, v160
	s_waitcnt lgkmcnt(0)
	v_mov_b32_e32 v25, s49
	v_cmp_lt_i32_e32 vcc, 15, v160
	v_and_or_b32 v24, v24, 7, s16
	v_lshlrev_b32_e32 v170, 6, v24
	v_cndmask_b32_e64 v159, v25, 0, vcc
	v_lshlrev_b32_e32 v25, 2, v160
	v_and_b32_e32 v25, 8, v25
	v_lshlrev_b32_e32 v24, 3, v160
	v_and_b32_e32 v171, 8, v24
	v_or_b32_e32 v24, 4, v25
	v_cndmask_b32_e32 v169, 0, v25, vcc
	v_cndmask_b32_e32 v174, 0, v24, vcc
	v_add_u32_e32 v172, v159, v171
	v_pk_mul_f32 v[26:27], v[20:21], v[56:57] op_sel_hi:[1,0]
	v_pk_mul_f32 v[24:25], v[22:23], v[56:57] op_sel_hi:[1,0]
	v_pk_mul_f32 v[22:23], v[52:53], v[56:57] op_sel_hi:[1,0]
	v_pk_mul_f32 v[20:21], v[54:55], v[56:57] op_sel_hi:[1,0]
	s_and_saveexec_b64 s[8:9], s[4:5]
	s_cbranch_execz .LBB0_504
	v_readlane_b32 s10, v248, 9
	v_cvt_pk_bf16_f32 v52, v26, v27
	v_cvt_pk_bf16_f32 v53, v24, v25
	v_bitop3_b32 v57, v174, v170, s10 bitop3:0xde
	v_bitop3_b32 v56, v169, v170, s10 bitop3:0xde
	v_lshlrev_b32_e32 v57, 4, v57
	v_or3_b32 v57, v57, v171, s65
	v_lshl_add_u32 v56, v56, 4, v172
	v_cvt_pk_bf16_f32 v54, v22, v23
	v_cvt_pk_bf16_f32 v55, v20, v21
	ds_write_b64 v56, v[52:53]
	v_add_u32_e32 v52, v159, v57
	ds_write_b64 v52, v[54:55]
	v_mov_b32_e32 v244, v56
	v_mov_b32_e32 v245, v52
	v_subrev_u32_e32 v247, 0x80, v52
	v_cndmask_b32_e32 v247, v52, v247, vcc

.LBB0_506:
	s_or_b64 exec, exec, s[8:9]
	v_pk_mul_f32 v[34:35], v[34:35], v[54:55] op_sel_hi:[1,0]
	s_waitcnt lgkmcnt(0)
	v_pk_mul_f32 v[32:33], v[30:31], v[54:55] op_sel_hi:[1,0]
	v_pk_mul_f32 v[30:31], v[28:29], v[54:55] op_sel_hi:[1,0]
	v_pk_mul_f32 v[28:29], v[52:53], v[54:55] op_sel_hi:[1,0]
	s_and_saveexec_b64 s[8:9], s[4:5]
	s_cbranch_execz .LBB0_508
	v_cvt_pk_bf16_f32 v52, v34, v35
	v_cvt_pk_bf16_f32 v53, v32, v33
	v_cvt_pk_bf16_f32 v54, v30, v31
	v_cvt_pk_bf16_f32 v55, v28, v29
	ds_write_b64 v244, v[52:53] offset:16
	ds_write_b64 v245, v[54:55] offset:16

.LBB0_510:
	s_or_b64 exec, exec, s[8:9]
	v_pk_mul_f32 v[42:43], v[42:43], v[64:65] op_sel_hi:[1,0]
	s_waitcnt lgkmcnt(0)
	v_pk_mul_f32 v[40:41], v[38:39], v[64:65] op_sel_hi:[1,0]
	v_pk_mul_f32 v[38:39], v[36:37], v[64:65] op_sel_hi:[1,0]
	v_pk_mul_f32 v[36:37], v[52:53], v[64:65] op_sel_hi:[1,0]
	s_and_saveexec_b64 s[8:9], s[4:5]
	s_cbranch_execz .LBB0_512
	v_cvt_pk_bf16_f32 v52, v42, v43
	v_cvt_pk_bf16_f32 v53, v40, v41
	v_cvt_pk_bf16_f32 v64, v38, v39
	v_cvt_pk_bf16_f32 v65, v36, v37
	ds_write_b64 v244, v[52:53] offset:32
	ds_write_b64 v245, v[64:65] offset:32

.LBB0_514:
	s_or_b64 exec, exec, s[8:9]
	v_pk_mul_f32 v[50:51], v[50:51], v[74:75] op_sel_hi:[1,0]
	s_waitcnt lgkmcnt(0)
	v_pk_mul_f32 v[48:49], v[46:47], v[74:75] op_sel_hi:[1,0]
	v_pk_mul_f32 v[46:47], v[44:45], v[74:75] op_sel_hi:[1,0]
	v_pk_mul_f32 v[44:45], v[68:69], v[74:75] op_sel_hi:[1,0]
	s_and_saveexec_b64 s[8:9], s[4:5]
	s_cbranch_execz .LBB0_516
	v_cvt_pk_bf16_f32 v68, v50, v51
	v_cvt_pk_bf16_f32 v69, v48, v49
	v_cvt_pk_bf16_f32 v74, v46, v47
	v_cvt_pk_bf16_f32 v75, v44, v45
	ds_write_b64 v244, v[68:69] offset:48
	ds_write_b64 v245, v[74:75] offset:48

.LBB0_518:
	s_or_b64 exec, exec, s[8:9]
	v_pk_mul_f32 v[68:69], v[68:69], v[86:87] op_sel_hi:[1,0]
	s_waitcnt lgkmcnt(0)
	v_pk_mul_f32 v[62:63], v[58:59], v[86:87] op_sel_hi:[1,0]
	v_pk_mul_f32 v[58:59], v[56:57], v[86:87] op_sel_hi:[1,0]
	v_pk_mul_f32 v[56:57], v[84:85], v[86:87] op_sel_hi:[1,0]
	s_and_saveexec_b64 s[8:9], s[4:5]
	s_cbranch_execz .LBB0_520
	v_cvt_pk_bf16_f32 v84, v68, v69
	v_cvt_pk_bf16_f32 v85, v62, v63
	v_cvt_pk_bf16_f32 v86, v58, v59
	v_cvt_pk_bf16_f32 v87, v56, v57
	ds_write_b64 v244, v[84:85] offset:64
	ds_write_b64 v247, v[86:87] offset:64

.LBB0_522:
	s_or_b64 exec, exec, s[8:9]
	v_pk_mul_f32 v[84:85], v[84:85], v[94:95] op_sel_hi:[1,0]
	s_waitcnt lgkmcnt(0)
	v_pk_mul_f32 v[72:73], v[66:67], v[94:95] op_sel_hi:[1,0]
	v_pk_mul_f32 v[66:67], v[54:55], v[94:95] op_sel_hi:[1,0]
	v_pk_mul_f32 v[54:55], v[92:93], v[94:95] op_sel_hi:[1,0]
	s_and_saveexec_b64 s[8:9], s[4:5]
	s_cbranch_execz .LBB0_524
	v_cvt_pk_bf16_f32 v92, v84, v85
	v_cvt_pk_bf16_f32 v93, v72, v73
	v_cvt_pk_bf16_f32 v94, v66, v67
	v_cvt_pk_bf16_f32 v95, v54, v55
	ds_write_b64 v244, v[92:93] offset:80
	ds_write_b64 v247, v[94:95] offset:80

.LBB0_526:
	s_or_b64 exec, exec, s[8:9]
	s_waitcnt lgkmcnt(0)
	v_pk_mul_f32 v[52:53], v[78:79], v[166:167] op_sel_hi:[1,0]
	v_pk_mul_f32 v[64:65], v[64:65], v[166:167] op_sel_hi:[1,0]
	v_pk_mul_f32 v[70:71], v[70:71], v[166:167] op_sel_hi:[1,0]
	v_pk_mul_f32 v[78:79], v[164:165], v[166:167] op_sel_hi:[1,0]
	s_and_saveexec_b64 s[8:9], s[4:5]
	s_cbranch_execz .LBB0_528
	v_cvt_pk_bf16_f32 v164, v52, v53
	v_cvt_pk_bf16_f32 v165, v64, v65
	v_cvt_pk_bf16_f32 v176, v70, v71
	v_cvt_pk_bf16_f32 v177, v78, v79
	ds_write_b64 v244, v[164:165] offset:96
	ds_write_b64 v247, v[176:177] offset:96

.LBB0_530:
	s_or_b64 exec, exec, s[8:9]
	s_waitcnt lgkmcnt(0)
	v_pk_mul_f32 v[60:61], v[82:83], v[86:87] op_sel_hi:[1,0]
	v_pk_mul_f32 v[74:75], v[74:75], v[86:87] op_sel_hi:[1,0]
	v_pk_mul_f32 v[76:77], v[76:77], v[86:87] op_sel_hi:[1,0]
	v_pk_mul_f32 v[80:81], v[80:81], v[86:87] op_sel_hi:[1,0]
	s_and_saveexec_b64 s[8:9], s[4:5]
	s_cbranch_execz .LBB0_532
	v_cvt_pk_bf16_f32 v82, v60, v61
	v_cvt_pk_bf16_f32 v83, v74, v75
	v_cvt_pk_bf16_f32 v86, v76, v77
	v_cvt_pk_bf16_f32 v87, v80, v81
	ds_write_b64 v244, v[82:83] offset:112
	ds_write_b64 v247, v[86:87] offset:112
